# prompt loops: the younger half (waves 4-7) sleeps after each tile barrier instead of the older half; no setprio (older waves win ties by age)
# baseline (speedup 1.0000x reference)
; template <int MODE, bool SAMPLE>
; __device__ __forceinline__ void attn_unit(const Params& p, char* lds, int b, int h, int qb) {
;     ...
;         if (j > jfirst) continue;
;         const int buf = par;
;         WRITET(buf, stg2[NS == 2 ? par : 0]);
;         if (j >= NS) LOADT(j - NS, stg2[NS == 2 ? par : 0]);
;         __syncthreads();
;         if (wact && j <= jd && var < 2) {
.LBB0_685:
	s_cmp_ge_i32 s20, s13
	s_waitcnt lgkmcnt(0)
	s_barrier
	s_cbranch_scc1 .LBB0_693
	v_readfirstlane_b32 s98, v183
	s_cmpk_lt_u32 s98, 0x100
	s_cbranch_scc1 .Lstg_0
	s_sleep 12

; template <int MODE, bool SAMPLE>
; __device__ __forceinline__ void attn_unit(const Params& p, char* lds, int b, int h, int qb) {
;     ...
;         if (j > jfirst) continue;
;         const int buf = par;
;         WRITET(buf, stg2[NS == 2 ? par : 0]);
;         if (j >= NS) LOADT(j - NS, stg2[NS == 2 ? par : 0]);
;         __syncthreads();
;         if (wact && j <= jd && var < 2) {
.LBB0_696:
	s_cmp_gt_i32 s20, s13
	s_waitcnt lgkmcnt(0)
	s_barrier
	s_cbranch_scc1 .LBB0_681
	v_readfirstlane_b32 s98, v183
	s_cmpk_lt_u32 s98, 0x100
	s_cbranch_scc1 .Lstg_1
	s_sleep 12

; template <int MODE, bool SAMPLE>
; __device__ __forceinline__ void attn_unit(const Params& p, char* lds, int b, int h, int qb) {
;     ...
;         if (j > jfirst) continue;
;         const int buf = par;
;         WRITET(buf, stg2[NS == 2 ? par : 0]);
;         if (j >= NS) LOADT(j - NS, stg2[NS == 2 ? par : 0]);
;         __syncthreads();
;         if (wact && j <= jd && var < 2) {
.LBB0_711:
	s_cmp_ge_u32 s33, s13
	s_waitcnt lgkmcnt(0)
	s_barrier
	s_cbranch_scc1 .LBB0_715
	v_readfirstlane_b32 s98, v183
	s_cmpk_lt_u32 s98, 0x100
	s_cbranch_scc1 .Lstg_2
	s_sleep 12

; template <int MODE, bool SAMPLE>
; __device__ __forceinline__ void attn_unit(const Params& p, char* lds, int b, int h, int qb) {
;     ...
;         if (j > jfirst) continue;
;         const int buf = par;
;         WRITET(buf, stg2[NS == 2 ? par : 0]);
;         if (j >= NS) LOADT(j - NS, stg2[NS == 2 ? par : 0]);
;         __syncthreads();
;         if (wact && j <= jd && var < 2) {
.LBB0_718:
	s_cmp_gt_u32 s33, s13
	s_waitcnt lgkmcnt(0)
	s_barrier
	s_cbranch_scc1 .LBB0_707
	v_readfirstlane_b32 s98, v183
	s_cmpk_lt_u32 s98, 0x100
	s_cbranch_scc1 .Lstg_3
	s_sleep 12

; template <int MODE, bool SAMPLE>
; __device__ __forceinline__ void attn_unit(const Params& p, char* lds, int b, int h, int qb) {
;     ...
;         if (j > jfirst) continue;
;         const int buf = par;
;         WRITET(buf, stg2[NS == 2 ? par : 0]);
;         if (j >= NS) LOADT(j - NS, stg2[NS == 2 ? par : 0]);
;         __syncthreads();
;         if (wact && j <= jd && var < 2) {
.LBB0_760:
	s_cmp_ge_i32 s18, s11
	s_waitcnt lgkmcnt(0)
	s_barrier
	s_cbranch_scc1 .LBB0_768
	v_readfirstlane_b32 s98, v183
	s_cmpk_lt_u32 s98, 0x100
	s_cbranch_scc1 .Lstg_4
	s_sleep 12

; template <int MODE, bool SAMPLE>
; __device__ __forceinline__ void attn_unit(const Params& p, char* lds, int b, int h, int qb) {
;     ...
;         if (j > jfirst) continue;
;         const int buf = par;
;         WRITET(buf, stg2[NS == 2 ? par : 0]);
;         if (j >= NS) LOADT(j - NS, stg2[NS == 2 ? par : 0]);
;         __syncthreads();
;         if (wact && j <= jd && var < 2) {
.LBB0_771:
	s_cmp_gt_i32 s18, s11
	s_waitcnt lgkmcnt(0)
	s_barrier
	s_cbranch_scc1 .LBB0_756
	v_readfirstlane_b32 s98, v183
	s_cmpk_lt_u32 s98, 0x100
	s_cbranch_scc1 .Lstg_5
	s_sleep 12

; template <int MODE, bool SAMPLE>
; __device__ __forceinline__ void attn_unit(const Params& p, char* lds, int b, int h, int qb) {
;     ...
;         if (j > jfirst) continue;
;         const int buf = par;
;         WRITET(buf, stg2[NS == 2 ? par : 0]);
;         if (j >= NS) LOADT(j - NS, stg2[NS == 2 ? par : 0]);
;         __syncthreads();
;         if (wact && j <= jd && var < 2) {
.LBB0_786:
	s_cmp_ge_u32 s33, s11
	s_waitcnt lgkmcnt(0)
	s_barrier
	s_cbranch_scc1 .LBB0_790
	v_readfirstlane_b32 s98, v183
	s_cmpk_lt_u32 s98, 0x100
	s_cbranch_scc1 .Lstg_6
	s_sleep 12

; template <int MODE, bool SAMPLE>
; __device__ __forceinline__ void attn_unit(const Params& p, char* lds, int b, int h, int qb) {
;     ...
;         if (j > jfirst) continue;
;         const int buf = par;
;         WRITET(buf, stg2[NS == 2 ? par : 0]);
;         if (j >= NS) LOADT(j - NS, stg2[NS == 2 ? par : 0]);
;         __syncthreads();
;         if (wact && j <= jd && var < 2) {
.LBB0_793:
	s_cmp_gt_u32 s33, s11
	s_waitcnt lgkmcnt(0)
	s_barrier
	s_cbranch_scc1 .LBB0_782
	v_readfirstlane_b32 s98, v183
	s_cmpk_lt_u32 s98, 0x100
	s_cbranch_scc1 .Lstg_7
	s_sleep 12
